# DSA attention K/V tiles prefetched two tiles ahead into a 4x32KiB LDS ring with counted vmcnt waits (on top of per-XCD DSA sub-lists)
# baseline (speedup 1.0000x reference)
.LBB0_939:
	s_lshl_b32 s0, s2, 8
	s_lshl_b32 s1, s28, 5
	v_and_b32_e32 v0, 31, v204
	s_add_i32 s4, s0, s1
	s_and_b32 s5, s29, 7
	v_ashrrev_i32_e32 v8, 5, v204
	v_or_b32_e32 v2, s4, v0
	v_mov_b64_e32 v[4:5], s[90:91]
	s_movk_i32 s0, 0x7200
	v_mad_i64_i32 v[4:5], s[0:1], v2, s0, v[4:5]
	s_lshl_b32 s58, s5, 8
	v_lshlrev_b32_e32 v6, 3, v8
	v_lshl_add_u64 v[4:5], v[4:5], 0, s[58:59]
	v_ashrrev_i32_e32 v7, 31, v6
	v_lshl_add_u64 v[4:5], v[6:7], 1, v[4:5]
	s_mov_b64 s[6:7], 0x25804800
	s_mov_b32 s1, 0x25804000
	s_lshl_b32 s0, s5, 7
	v_lshl_add_u64 v[6:7], v[4:5], 0, s[6:7]
	v_add_co_u32_e32 v4, vcc, s1, v4
	s_lshl_b32 s1, s5, 21
	s_barrier
	v_addc_co_u32_e32 v5, vcc, 0, v5, vcc
	global_load_dwordx4 v[98:101], v[6:7], off offset:32
	global_load_dwordx4 v[102:105], v[6:7], off offset:64
	global_load_dwordx4 v[106:109], v[6:7], off offset:96
	global_load_dwordx4 v[110:113], v[6:7], off offset:128
	global_load_dwordx4 v[114:117], v[6:7], off offset:160
	global_load_dwordx4 v[118:121], v[6:7], off offset:192
	global_load_dwordx4 v[122:125], v[4:5], off offset:2048
	global_load_dwordx4 v[126:129], v[6:7], off offset:224
	v_lshlrev_b32_e32 v4, 3, v204
	s_add_u32 s6, s90, s1
	v_ashrrev_i32_e32 v5, 31, v4
	s_addc_u32 s7, s91, 0
	v_lshl_add_u64 v[4:5], v[4:5], 1, s[6:7]
	s_mov_b64 s[6:7], 0x73500000
	v_lshl_add_u64 v[132:133], v[4:5], 0, s[6:7]
	s_mov_b64 s[6:7], 0x74500000
	v_lshl_add_u64 v[134:135], v[4:5], 0, s[6:7]
	s_lshl_b32 s6, s28, 1
	s_ashr_i32 s7, s6, 31
	s_lshl_b32 s1, s28, 11
	s_lshl_b64 s[8:9], s[6:7], 10
	s_add_i32 s1, s1, 0
	v_lshl_add_u64 v[4:5], v[132:133], 0, s[8:9]
	s_mov_b32 m0, s1
	v_ashrrev_i32_e32 v3, 31, v2
	global_load_lds_dwordx4 v[4:5], off
	v_lshl_add_u64 v[4:5], v[134:135], 0, s[8:9]
	s_or_b32 s8, s6, 1
	s_ashr_i32 s9, s8, 31
	s_lshl_b32 s5, s8, 10
	s_add_i32 m0, s1, 0x4000
	s_lshl_b64 s[10:11], s[8:9], 10
	s_add_i32 s5, s5, 0
	global_load_lds_dwordx4 v[4:5], off
	v_lshl_add_u64 v[4:5], v[132:133], 0, s[10:11]
	s_mov_b32 m0, s5
	v_lshlrev_b64 v[2:3], 10, v[2:3]
	global_load_lds_dwordx4 v[4:5], off
	v_lshl_add_u64 v[4:5], v[134:135], 0, s[10:11]
	s_add_i32 m0, s5, 0x4000
	s_lshl_b32 s2, s2, 2
	global_load_lds_dwordx4 v[4:5], off
	s_add_i32 s10, s6, 16
	s_ashr_i32 s11, s10, 31
	s_lshl_b64 s[10:11], s[10:11], 10
	s_add_i32 s9, s1, 0x8000
	v_lshl_add_u64 v[178:179], v[132:133], 0, s[10:11]
	s_mov_b32 m0, s9
	s_nop 0
	global_load_lds_dwordx4 v[178:179], off
	v_lshl_add_u64 v[178:179], v[134:135], 0, s[10:11]
	s_add_i32 m0, s9, 0x4000
	s_add_i32 s10, s6, 17
	s_ashr_i32 s11, s10, 31
	s_lshl_b64 s[10:11], s[10:11], 10
	global_load_lds_dwordx4 v[178:179], off
	v_lshl_add_u64 v[178:179], v[132:133], 0, s[10:11]
	s_add_i32 m0, s9, 0x400
	s_nop 0
	global_load_lds_dwordx4 v[178:179], off
	v_lshl_add_u64 v[178:179], v[134:135], 0, s[10:11]
	s_add_i32 m0, s9, 0x4400
	s_nop 0
	global_load_lds_dwordx4 v[178:179], off
	v_lshl_add_u64 v[2:3], s[90:91], 0, v[2:3]
	s_mov_b64 s[8:9], 0x72d00004
	s_lshl_b32 s3, s3, 2
	v_mov_b32_e32 v138, 0
	s_add_i32 s2, s2, 4
	v_lshl_add_u32 v131, v204, 4, 0
	v_lshlrev_b32_e32 v130, 2, v8
	v_lshl_add_u64 v[136:137], v[2:3], 0, s[8:9]
	s_add_i32 s6, s6, 17
	s_sub_i32 s3, 0, s3
	s_mov_b32 s5, 0x8000
	s_movk_i32 s8, 0xff80
	v_mov_b32_e32 v2, 0
	v_mov_b32_e32 v3, v138
	v_mov_b32_e32 v4, v138
	v_mov_b32_e32 v5, v138
	v_mov_b32_e32 v6, v138
	v_mov_b32_e32 v7, v138
	v_mov_b32_e32 v8, v138
	v_mov_b32_e32 v9, v138
	v_mov_b32_e32 v10, v138
	v_mov_b32_e32 v11, v138
	v_mov_b32_e32 v12, v138
	v_mov_b32_e32 v13, v138
	v_mov_b32_e32 v14, v138
	v_mov_b32_e32 v15, v138
	v_mov_b32_e32 v16, v138
	v_mov_b32_e32 v17, v138
	v_mov_b32_e32 v18, 0
	v_mov_b32_e32 v19, v138
	v_mov_b32_e32 v20, v138
	v_mov_b32_e32 v21, v138
	v_mov_b32_e32 v22, v138
	v_mov_b32_e32 v23, v138
	v_mov_b32_e32 v24, v138
	v_mov_b32_e32 v25, v138
	v_mov_b32_e32 v26, v138
	v_mov_b32_e32 v27, v138
	v_mov_b32_e32 v28, v138
	v_mov_b32_e32 v29, v138
	v_mov_b32_e32 v30, v138
	v_mov_b32_e32 v31, v138
	v_mov_b32_e32 v32, v138
	v_mov_b32_e32 v33, v138
	v_mov_b32_e32 v34, 0
	v_mov_b32_e32 v35, v138
	v_mov_b32_e32 v36, v138
	v_mov_b32_e32 v37, v138
	v_mov_b32_e32 v38, v138
	v_mov_b32_e32 v39, v138
	v_mov_b32_e32 v40, v138
	v_mov_b32_e32 v41, v138
	v_mov_b32_e32 v42, v138
	v_mov_b32_e32 v43, v138
	v_mov_b32_e32 v44, v138
	v_mov_b32_e32 v45, v138
	v_mov_b32_e32 v46, v138
	v_mov_b32_e32 v47, v138
	v_mov_b32_e32 v48, v138
	v_mov_b32_e32 v49, v138
	v_mov_b32_e32 v50, 0
	v_mov_b32_e32 v51, v138
	v_mov_b32_e32 v52, v138
	v_mov_b32_e32 v53, v138
	v_mov_b32_e32 v54, v138
	v_mov_b32_e32 v55, v138
	v_mov_b32_e32 v56, v138
	v_mov_b32_e32 v57, v138
	v_mov_b32_e32 v58, v138
	v_mov_b32_e32 v59, v138
	v_mov_b32_e32 v60, v138
	v_mov_b32_e32 v61, v138
	v_mov_b32_e32 v62, v138
	v_mov_b32_e32 v63, v138
	v_mov_b32_e32 v64, v138
	v_mov_b32_e32 v65, v138
	global_load_dwordx2 v[176:177], v[136:137], off offset:-4
	v_lshl_add_u64 v[136:137], v[136:137], 0, 8
	s_waitcnt vmcnt(0) lgkmcnt(0)
	s_barrier
	s_cmp_lt_u32 s28, 4
	s_cbranch_scc1 .Ldsa0_pre
	s_barrier

.LBB0_940:
	s_add_i32 s7, s5, 0xffff8000
	s_and_b32 s7, s7, 0x18000
	v_add_u32_e32 v139, s7, v131
	ds_read_b128 v[66:69], v139
	ds_read_b128 v[82:85], v139 offset:1024
	s_add_i32 s6, s6, 16
	s_add_i32 s5, s5, 0x8000
	s_add_i32 s8, s8, 1
	s_waitcnt lgkmcnt(0)
	v_mfma_f32_32x32x16_bf16 v[66:81], v[66:69], v[122:125], 0
	v_mfma_f32_32x32x16_bf16 v[66:81], v[82:85], v[98:101], v[66:81]
	ds_read_b128 v[82:85], v139 offset:2048
	ds_read_b128 v[86:89], v139 offset:3072
	s_waitcnt lgkmcnt(0)
	v_mfma_f32_32x32x16_bf16 v[66:81], v[82:85], v[102:105], v[66:81]
	v_mfma_f32_32x32x16_bf16 v[66:81], v[86:89], v[106:109], v[66:81]
	ds_read_b128 v[82:85], v139 offset:4096
	ds_read_b128 v[86:89], v139 offset:5120
	s_waitcnt lgkmcnt(0)
	v_mfma_f32_32x32x16_bf16 v[66:81], v[82:85], v[110:113], v[66:81]
	v_mfma_f32_32x32x16_bf16 v[66:81], v[86:89], v[114:117], v[66:81]
	ds_read_b128 v[82:85], v139 offset:6144
	ds_read_b128 v[86:89], v139 offset:7168
	s_waitcnt lgkmcnt(0)
	v_mfma_f32_32x32x16_bf16 v[66:81], v[82:85], v[118:121], v[66:81]
	ds_read_b128 v[82:85], v139 offset:8192
	ds_read_b128 v[140:143], v139 offset:9216
	v_mfma_f32_32x32x16_bf16 v[66:81], v[86:89], v[126:129], v[66:81]
	s_waitcnt lgkmcnt(0)
	v_mfma_f32_32x32x16_bf16 v[82:97], v[82:85], v[122:125], 0
	s_nop 9
	v_min_f32_e32 v66, 0x42700000, v66
	v_exp_f32_e32 v66, v66
	v_min_f32_e32 v74, 0x42700000, v74
	v_min_f32_e32 v75, 0x42700000, v75
	v_mfma_f32_32x32x16_bf16 v[82:97], v[140:143], v[98:101], v[82:97]
	ds_read_b128 v[140:143], v139 offset:10240
	ds_read_b128 v[144:147], v139 offset:11264
	v_exp_f32_e32 v74, v74
	v_min_f32_e32 v76, 0x42700000, v76
	v_min_f32_e32 v77, 0x42700000, v77
	v_exp_f32_e32 v76, v76
	s_waitcnt lgkmcnt(0)
	v_mfma_f32_32x32x16_bf16 v[82:97], v[140:143], v[102:105], v[82:97]
	v_min_f32_e32 v78, 0x42700000, v78
	v_min_f32_e32 v79, 0x42700000, v79
	v_exp_f32_e32 v78, v78
	v_mfma_f32_32x32x16_bf16 v[82:97], v[144:147], v[106:109], v[82:97]
	ds_read_b128 v[140:143], v139 offset:12288
	ds_read_b128 v[144:147], v139 offset:13312
	v_min_f32_e32 v80, 0x42700000, v80
	v_min_f32_e32 v81, 0x42700000, v81
	v_exp_f32_e32 v80, v80
	s_waitcnt lgkmcnt(0)
	v_mfma_f32_32x32x16_bf16 v[82:97], v[140:143], v[110:113], v[82:97]
	v_mfma_f32_32x32x16_bf16 v[82:97], v[144:147], v[114:117], v[82:97]
	ds_read_b128 v[140:143], v139 offset:14336
	ds_read_b128 v[144:147], v139 offset:15360
	ds_read_b128 v[148:151], v139 offset:20480
	ds_read_b128 v[156:159], v139 offset:24576
	ds_read_b128 v[160:163], v139 offset:25600
	s_waitcnt lgkmcnt(0)
	v_mfma_f32_32x32x16_bf16 v[82:97], v[140:143], v[118:121], v[82:97]
	v_lshrrev_b32_e32 v140, v130, v176
	v_lshrrev_b32_e32 v141, v130, v177
	global_load_dwordx2 v[176:177], v[136:137], off offset:-4
	v_lshl_add_u64 v[136:137], v[136:137], 0, 8
	v_mfma_f32_32x32x16_bf16 v[82:97], v[144:147], v[126:129], v[82:97]
	s_barrier
	s_add_i32 s7, s8, 0x81
	s_cmp_ge_u32 s7, s2
	s_cbranch_scc1 .Ldsa0_nodma
	s_add_i32 s10, s6, -1
	s_and_b32 s7, s5, 0x18000
	s_ashr_i32 s11, s10, 31
	s_lshl_b64 s[10:11], s[10:11], 10
	s_add_i32 s9, s1, s7
	v_lshl_add_u64 v[178:179], v[132:133], 0, s[10:11]
	s_mov_b32 m0, s9
	s_ashr_i32 s7, s6, 31
	global_load_lds_dwordx4 v[178:179], off
	v_lshl_add_u64 v[178:179], v[134:135], 0, s[10:11]
	s_add_i32 m0, s9, 0x4000
	s_lshl_b64 s[10:11], s[6:7], 10
	global_load_lds_dwordx4 v[178:179], off
	v_lshl_add_u64 v[178:179], v[132:133], 0, s[10:11]
	s_add_i32 m0, s9, 0x400
	s_nop 0
	global_load_lds_dwordx4 v[178:179], off
	v_lshl_add_u64 v[178:179], v[134:135], 0, s[10:11]
	s_add_i32 m0, s9, 0x4400
	s_nop 0
	global_load_lds_dwordx4 v[178:179], off
.Ldsa0_nodma:
	v_and_b32_e32 v142, 1, v140
	v_cmp_eq_u32_e32 vcc, 1, v142
	s_nop 1
	v_cndmask_b32_e32 v168, 0, v66, vcc
	v_and_b32_e32 v66, 1, v141
	s_nop 5
	v_min_f32_e32 v82, 0x42700000, v82
	v_exp_f32_e32 v82, v82
	v_cmp_eq_u32_e32 vcc, 1, v66
	v_min_f32_e32 v66, 0x42700000, v67
	v_exp_f32_e32 v66, v66
	v_cndmask_b32_e32 v169, 0, v82, vcc
	v_min_f32_e32 v67, 0x42700000, v83
	v_and_b32_e32 v82, 2, v140
	v_cmp_ne_u32_e32 vcc, 0, v82
	v_exp_f32_e32 v67, v67
	v_and_b32_e32 v83, 0x800, v140
	v_cndmask_b32_e32 v170, 0, v66, vcc
	v_and_b32_e32 v66, 2, v141
	v_cmp_ne_u32_e32 vcc, 0, v66
	v_min_f32_e32 v66, 0x42700000, v68
	v_exp_f32_e32 v66, v66
	v_cndmask_b32_e32 v171, 0, v67, vcc
	v_min_f32_e32 v67, 0x42700000, v84
	v_and_b32_e32 v68, 4, v140
	v_exp_f32_e32 v67, v67
	v_cmp_ne_u32_e32 vcc, 0, v68
	v_and_b32_e32 v68, 8, v140
	s_nop 0
	v_cndmask_b32_e32 v172, 0, v66, vcc
	v_and_b32_e32 v66, 4, v141
	v_cmp_ne_u32_e32 vcc, 0, v66
	v_min_f32_e32 v66, 0x42700000, v69
	v_cndmask_b32_e32 v173, 0, v67, vcc
	v_exp_f32_e32 v66, v66
	v_min_f32_e32 v67, 0x42700000, v85
	v_exp_f32_e32 v67, v67
	v_cmp_ne_u32_e32 vcc, 0, v68
	v_and_b32_e32 v85, 0x20000, v140
	s_nop 0
	v_cndmask_b32_e32 v174, 0, v66, vcc
	v_and_b32_e32 v66, 8, v141
	v_cmp_ne_u32_e32 vcc, 0, v66
	v_min_f32_e32 v66, 0x42700000, v70
	v_cndmask_b32_e32 v175, 0, v67, vcc
	v_min_f32_e32 v67, 0x42700000, v86
	v_exp_f32_e32 v68, v67
	v_min_f32_e32 v67, 0x42700000, v71
	v_exp_f32_e32 v66, v66
	v_exp_f32_e32 v69, v67
	v_min_f32_e32 v67, 0x42700000, v87
	v_exp_f32_e32 v70, v67
	v_and_b32_e32 v67, 0x100, v140
	v_and_b32_e32 v71, 0x200, v140
	v_cmp_ne_u32_e32 vcc, 0, v67
	v_and_b32_e32 v87, 0x80000, v140
	s_nop 0
	v_cndmask_b32_e32 v67, 0, v66, vcc
	v_cmp_ne_u32_e32 vcc, 0, v71
	v_and_b32_e32 v71, 0x200, v141
	s_nop 0
	v_cndmask_b32_e32 v66, 0, v69, vcc
	v_and_b32_e32 v69, 0x100, v141
	v_cmp_ne_u32_e32 vcc, 0, v69
	s_nop 1
	v_cndmask_b32_e32 v69, 0, v68, vcc
	v_cmp_ne_u32_e32 vcc, 0, v71
	v_min_f32_e32 v71, 0x42700000, v88
	v_cndmask_b32_e32 v68, 0, v70, vcc
	v_max_f32_e32 v70, v72, v72
	v_exp_f32_e32 v72, v71
	v_min_f32_e32 v71, 0x42700000, v73
	v_min_f32_e32 v70, 0x42700000, v70
	v_exp_f32_e32 v70, v70
	v_exp_f32_e32 v73, v71
	v_min_f32_e32 v71, 0x42700000, v89
	v_exp_f32_e32 v82, v71
	v_and_b32_e32 v71, 0x400, v140
	v_cmp_ne_u32_e32 vcc, 0, v71
	v_and_b32_e32 v89, 0x2000000, v140
	s_nop 0
	v_cndmask_b32_e32 v71, 0, v70, vcc
	v_cmp_ne_u32_e32 vcc, 0, v83
	v_and_b32_e32 v83, 0x800, v141
	s_nop 0
	v_cndmask_b32_e32 v70, 0, v73, vcc
	v_and_b32_e32 v73, 0x400, v141
	v_cmp_ne_u32_e32 vcc, 0, v73
	s_nop 1
	v_cndmask_b32_e32 v73, 0, v72, vcc
	v_cmp_ne_u32_e32 vcc, 0, v83
	v_exp_f32_e32 v83, v75
	v_min_f32_e32 v75, 0x42700000, v91
	v_cndmask_b32_e32 v72, 0, v82, vcc
	v_min_f32_e32 v82, 0x42700000, v90
	v_exp_f32_e32 v84, v75
	v_and_b32_e32 v75, 0x10000, v140
	v_exp_f32_e32 v82, v82
	v_cmp_ne_u32_e32 vcc, 0, v75
	v_and_b32_e32 v91, 0x8000000, v140
	v_pk_mov_b32 v[152:153], v[72:73], v[72:73] op_sel:[1,0]
	v_cndmask_b32_e32 v75, 0, v74, vcc
	v_cmp_ne_u32_e32 vcc, 0, v85
	v_and_b32_e32 v85, 0x20000, v141
	s_nop 0
	v_cndmask_b32_e32 v74, 0, v83, vcc
	v_and_b32_e32 v83, 0x10000, v141
	v_cmp_ne_u32_e32 vcc, 0, v83
	s_nop 1
	v_cndmask_b32_e32 v83, 0, v82, vcc
	v_cmp_ne_u32_e32 vcc, 0, v85
	v_exp_f32_e32 v85, v77
	v_min_f32_e32 v77, 0x42700000, v93
	v_cndmask_b32_e32 v82, 0, v84, vcc
	v_min_f32_e32 v84, 0x42700000, v92
	v_exp_f32_e32 v86, v77
	v_and_b32_e32 v77, 0x40000, v140
	v_exp_f32_e32 v84, v84
	v_cmp_ne_u32_e32 vcc, 0, v77
	v_pk_mov_b32 v[92:93], v[66:67], v[66:67] op_sel:[1,0]
	v_pk_add_f32 v[66:67], v[66:67], v[68:69]
	v_cndmask_b32_e32 v77, 0, v76, vcc
	v_cmp_ne_u32_e32 vcc, 0, v87
	v_and_b32_e32 v87, 0x80000, v141
	v_cvt_pk_bf16_f32 v92, v92, v93
	v_cndmask_b32_e32 v76, 0, v85, vcc
	v_and_b32_e32 v85, 0x40000, v141
	v_cmp_ne_u32_e32 vcc, 0, v85
	s_nop 1
	v_cndmask_b32_e32 v85, 0, v84, vcc
	v_cmp_ne_u32_e32 vcc, 0, v87
	v_exp_f32_e32 v87, v79
	v_min_f32_e32 v79, 0x42700000, v95
	v_cndmask_b32_e32 v84, 0, v86, vcc
	v_min_f32_e32 v86, 0x42700000, v94
	v_exp_f32_e32 v88, v79
	v_and_b32_e32 v79, 0x1000000, v140
	v_exp_f32_e32 v86, v86
	v_cmp_ne_u32_e32 vcc, 0, v79
	v_pk_mov_b32 v[94:95], v[70:71], v[70:71] op_sel:[1,0]
	s_nop 0
	v_cndmask_b32_e32 v79, 0, v78, vcc
	v_cmp_ne_u32_e32 vcc, 0, v89
	v_and_b32_e32 v89, 0x2000000, v141
	v_cvt_pk_bf16_f32 v93, v94, v95
	v_cndmask_b32_e32 v78, 0, v87, vcc
	v_and_b32_e32 v87, 0x1000000, v141
	v_cmp_ne_u32_e32 vcc, 0, v87
	v_pk_mov_b32 v[94:95], v[74:75], v[74:75] op_sel:[1,0]
	s_nop 0
	v_cndmask_b32_e32 v87, 0, v86, vcc
	v_cmp_ne_u32_e32 vcc, 0, v89
	v_exp_f32_e32 v89, v81
	v_min_f32_e32 v81, 0x42700000, v97
	v_cndmask_b32_e32 v86, 0, v88, vcc
	v_min_f32_e32 v88, 0x42700000, v96
	v_exp_f32_e32 v90, v81
	v_and_b32_e32 v81, 0x4000000, v140
	v_exp_f32_e32 v88, v88
	v_cmp_ne_u32_e32 vcc, 0, v81
	v_pk_mov_b32 v[96:97], v[76:77], v[76:77] op_sel:[1,0]
	v_cvt_pk_bf16_f32 v94, v94, v95
	v_cndmask_b32_e32 v81, 0, v80, vcc
	v_cmp_ne_u32_e32 vcc, 0, v91
	v_and_b32_e32 v91, 0x8000000, v141
	v_cvt_pk_bf16_f32 v95, v96, v97
	v_cndmask_b32_e32 v80, 0, v89, vcc
	v_and_b32_e32 v89, 0x4000000, v141
	v_cmp_ne_u32_e32 vcc, 0, v89
	s_cmp_lt_u32 s28, 4
	s_cbranch_scc1 .Ldsa0_b2
	s_add_i32 s7, s8, 0x81
	s_cmp_ge_u32 s7, s2
	s_cbranch_scc1 .Ldsa0_b2z
	s_waitcnt vmcnt(4)
	s_branch .Ldsa0_b2

.Ldsa0_b2:
	s_barrier
	ds_read_b128 v[140:143], v139 offset:16384
	v_pk_mov_b32 v[96:97], v[78:79], v[78:79] op_sel:[1,0]
	v_cndmask_b32_e32 v89, 0, v88, vcc
	v_cmp_ne_u32_e32 vcc, 0, v91
	v_cvt_pk_bf16_f32 v91, v172, v174
	v_pk_mov_b32 v[144:145], v[80:81], v[80:81] op_sel:[1,0]
	v_cndmask_b32_e32 v88, 0, v90, vcc
	v_cvt_pk_bf16_f32 v90, v168, v170
	v_cvt_pk_bf16_f32 v96, v96, v97
	v_cvt_pk_bf16_f32 v97, v144, v145
	ds_read_b128 v[144:147], v139 offset:17408
	s_waitcnt lgkmcnt(1)
	v_mfma_f32_32x32x16_bf16 v[2:17], v[90:93], v[140:143], v[2:17]
	v_pk_mov_b32 v[142:143], v[68:69], v[68:69] op_sel:[1,0]
	v_cvt_pk_bf16_f32 v140, v169, v171
	v_cvt_pk_bf16_f32 v142, v142, v143
	v_cvt_pk_bf16_f32 v143, v152, v153
	ds_read_b128 v[152:155], v139 offset:21504
	v_cvt_pk_bf16_f32 v141, v173, v175
	v_pk_add_f32 v[68:69], v[70:71], v[72:73]
	v_mfma_f32_32x32x16_bf16 v[2:17], v[94:97], v[148:151], v[2:17]
	v_pk_mov_b32 v[148:149], v[82:83], v[82:83] op_sel:[1,0]
	v_pk_mov_b32 v[150:151], v[84:85], v[84:85] op_sel:[1,0]
	v_cvt_pk_bf16_f32 v148, v148, v149
	v_cvt_pk_bf16_f32 v149, v150, v151
	v_pk_mov_b32 v[150:151], v[86:87], v[86:87] op_sel:[1,0]
	v_pk_add_f32 v[70:71], v[74:75], v[82:83]
	v_cvt_pk_bf16_f32 v150, v150, v151
	s_waitcnt lgkmcnt(1)
	v_mfma_f32_32x32x16_bf16 v[18:33], v[90:93], v[144:147], v[18:33]
	v_add_f32_e64 v74, v78, v86
	v_add_f32_e64 v75, v79, v87
	v_add_f32_e64 v72, v76, v84
	v_add_f32_e64 v73, v77, v85
	v_add_f32_e64 v76, v80, v88
	v_add_f32_e64 v77, v81, v89
	v_mfma_f32_32x32x16_bf16 v[2:17], v[140:143], v[156:159], v[2:17]
	v_pk_mov_b32 v[156:157], v[88:89], v[88:89] op_sel:[1,0]
	s_nop 0
	v_cvt_pk_bf16_f32 v151, v156, v157
	ds_read_b128 v[156:159], v139 offset:28672
	ds_read_b128 v[164:167], v139 offset:29696
	s_waitcnt lgkmcnt(2)
	v_mfma_f32_32x32x16_bf16 v[18:33], v[94:97], v[152:155], v[18:33]
	ds_read_b128 v[144:147], v139 offset:18432
	ds_read_b128 v[152:155], v139 offset:19456
	s_waitcnt lgkmcnt(1)
	v_mfma_f32_32x32x16_bf16 v[34:49], v[90:93], v[144:147], v[34:49]
	v_mfma_f32_32x32x16_bf16 v[2:17], v[148:151], v[156:159], v[2:17]
	ds_read_b128 v[144:147], v139 offset:22528
	ds_read_b128 v[156:159], v139 offset:23552
	s_waitcnt lgkmcnt(1)
	v_mfma_f32_32x32x16_bf16 v[34:49], v[94:97], v[144:147], v[34:49]
	v_mfma_f32_32x32x16_bf16 v[50:65], v[90:93], v[152:155], v[50:65]
	v_mfma_f32_32x32x16_bf16 v[18:33], v[140:143], v[160:163], v[18:33]
	ds_read_b128 v[144:147], v139 offset:26624
	ds_read_b128 v[160:163], v139 offset:27648
	s_waitcnt lgkmcnt(1)
	v_mfma_f32_32x32x16_bf16 v[34:49], v[140:143], v[144:147], v[34:49]
	v_mfma_f32_32x32x16_bf16 v[50:65], v[94:97], v[156:159], v[50:65]
	v_mfma_f32_32x32x16_bf16 v[18:33], v[148:151], v[164:167], v[18:33]
	ds_read_b128 v[144:147], v139 offset:30720
	ds_read_b128 v[164:167], v139 offset:31744
	v_add_f32_e32 v139, v168, v169
	v_add_f32_e32 v78, v138, v139
	s_add_i32 s7, s8, 0x81
	s_cmp_ge_u32 s7, s2
	s_cbranch_scc1 .Ldsa0_b3z
	s_waitcnt vmcnt(4) lgkmcnt(0)
	s_branch .Ldsa0_b3

.Ldsa0_b3:
	s_barrier
	v_mfma_f32_32x32x16_bf16 v[34:49], v[148:151], v[144:147], v[34:49]
	v_add_f32_e32 v144, v170, v171
	v_add_f32_e32 v145, v172, v173
	v_add_f32_e32 v78, v144, v78
	v_add_f32_e32 v146, v174, v175
	v_add_f32_e32 v78, v145, v78
	v_add_f32_e32 v78, v146, v78
	v_add_f32_e32 v67, v67, v78
	v_mfma_f32_32x32x16_bf16 v[50:65], v[140:143], v[160:163], v[50:65]
	v_add_f32_e32 v66, v66, v67
	v_add_f32_e32 v66, v69, v66
	v_add_f32_e32 v66, v68, v66
	v_add_f32_e32 v66, v71, v66
	v_add_f32_e32 v66, v70, v66
	v_add_f32_e32 v66, v73, v66
	v_add_f32_e32 v66, v72, v66
	v_mfma_f32_32x32x16_bf16 v[50:65], v[148:151], v[164:167], v[50:65]
	v_add_f32_e32 v66, v75, v66
	v_add_f32_e32 v66, v74, v66
	v_add_f32_e32 v66, v77, v66
	v_add_f32_e32 v138, v76, v66
	s_cmp_eq_u32 s3, s8
	s_cbranch_scc1 .LBB0_943
.LBB0_941:
	s_branch .LBB0_940
.LBB0_943:
	s_cmp_lt_u32 s28, 4
	s_cbranch_scc0 .Ldsa0_post
	s_barrier

.LBB0_2560:
	s_sub_i32 s2, 31, s3
	s_lshl_b32 s0, s2, 8
	s_lshl_b32 s1, s28, 5
	v_and_b32_e32 v0, 31, v204
	s_add_i32 s4, s0, s1
	s_and_b32 s5, s29, 7
	v_ashrrev_i32_e32 v8, 5, v204
	v_or_b32_e32 v2, s4, v0
	v_mov_b64_e32 v[4:5], s[90:91]
	v_mad_i64_i32 v[4:5], s[0:1], v2, s41, v[4:5]
	s_lshl_b32 s58, s5, 8
	v_lshlrev_b32_e32 v6, 3, v8
	v_lshl_add_u64 v[4:5], v[4:5], 0, s[58:59]
	v_ashrrev_i32_e32 v7, 31, v6
	v_lshl_add_u64 v[4:5], v[6:7], 1, v[4:5]
	s_mov_b64 s[6:7], 0x25804800
	s_mov_b32 s1, 0x25804000
	s_lshl_b32 s0, s5, 7
	v_lshl_add_u64 v[6:7], v[4:5], 0, s[6:7]
	v_add_co_u32_e32 v4, vcc, s1, v4
	s_lshl_b32 s1, s5, 21
	s_barrier
	v_addc_co_u32_e32 v5, vcc, 0, v5, vcc
	global_load_dwordx4 v[98:101], v[6:7], off offset:32
	global_load_dwordx4 v[102:105], v[6:7], off offset:64
	global_load_dwordx4 v[106:109], v[6:7], off offset:96
	global_load_dwordx4 v[110:113], v[6:7], off offset:128
	global_load_dwordx4 v[114:117], v[6:7], off offset:160
	global_load_dwordx4 v[118:121], v[6:7], off offset:192
	global_load_dwordx4 v[122:125], v[4:5], off offset:2048
	global_load_dwordx4 v[126:129], v[6:7], off offset:224
	v_lshlrev_b32_e32 v4, 3, v204
	s_add_u32 s6, s90, s1
	v_ashrrev_i32_e32 v5, 31, v4
	s_addc_u32 s7, s91, 0
	v_lshl_add_u64 v[4:5], v[4:5], 1, s[6:7]
	s_mov_b64 s[6:7], 0x73500000
	v_lshl_add_u64 v[132:133], v[4:5], 0, s[6:7]
	s_mov_b64 s[6:7], 0x74500000
	v_lshl_add_u64 v[134:135], v[4:5], 0, s[6:7]
	s_lshl_b32 s6, s28, 1
	s_ashr_i32 s7, s6, 31
	s_lshl_b32 s1, s28, 11
	s_lshl_b64 s[8:9], s[6:7], 10
	s_add_i32 s1, s1, 0
	v_lshl_add_u64 v[4:5], v[132:133], 0, s[8:9]
	s_mov_b32 m0, s1
	v_ashrrev_i32_e32 v3, 31, v2
	global_load_lds_dwordx4 v[4:5], off
	v_lshl_add_u64 v[4:5], v[134:135], 0, s[8:9]
	s_or_b32 s8, s6, 1
	s_ashr_i32 s9, s8, 31
	s_lshl_b32 s5, s8, 10
	s_add_i32 m0, s1, 0x4000
	s_lshl_b64 s[10:11], s[8:9], 10
	s_add_i32 s5, s5, 0
	global_load_lds_dwordx4 v[4:5], off
	v_lshl_add_u64 v[4:5], v[132:133], 0, s[10:11]
	s_mov_b32 m0, s5
	v_lshlrev_b64 v[2:3], 10, v[2:3]
	global_load_lds_dwordx4 v[4:5], off
	v_lshl_add_u64 v[4:5], v[134:135], 0, s[10:11]
	s_add_i32 m0, s5, 0x4000
	s_lshl_b32 s2, s2, 2
	global_load_lds_dwordx4 v[4:5], off
	s_add_i32 s10, s6, 16
	s_ashr_i32 s11, s10, 31
	s_lshl_b64 s[10:11], s[10:11], 10
	s_add_i32 s9, s1, 0x8000
	v_lshl_add_u64 v[178:179], v[132:133], 0, s[10:11]
	s_mov_b32 m0, s9
	s_nop 0
	global_load_lds_dwordx4 v[178:179], off
	v_lshl_add_u64 v[178:179], v[134:135], 0, s[10:11]
	s_add_i32 m0, s9, 0x4000
	s_add_i32 s10, s6, 17
	s_ashr_i32 s11, s10, 31
	s_lshl_b64 s[10:11], s[10:11], 10
	global_load_lds_dwordx4 v[178:179], off
	v_lshl_add_u64 v[178:179], v[132:133], 0, s[10:11]
	s_add_i32 m0, s9, 0x400
	s_nop 0
	global_load_lds_dwordx4 v[178:179], off
	v_lshl_add_u64 v[178:179], v[134:135], 0, s[10:11]
	s_add_i32 m0, s9, 0x4400
	s_nop 0
	global_load_lds_dwordx4 v[178:179], off
	v_lshl_add_u64 v[2:3], s[90:91], 0, v[2:3]
	s_mov_b64 s[8:9], 0x72d00004
	s_lshl_b32 s3, s3, 2
	v_mov_b32_e32 v138, 0
	s_add_i32 s2, s2, 4
	v_lshl_add_u32 v131, v204, 4, 0
	v_lshlrev_b32_e32 v130, 2, v8
	v_lshl_add_u64 v[136:137], v[2:3], 0, s[8:9]
	s_add_i32 s6, s6, 17
	s_sub_i32 s3, 0, s3
	s_mov_b32 s5, 0x8000
	s_movk_i32 s8, 0xff80
	v_mov_b32_e32 v2, 0
	v_mov_b32_e32 v3, v138
	v_mov_b32_e32 v4, v138
	v_mov_b32_e32 v5, v138
	v_mov_b32_e32 v6, v138
	v_mov_b32_e32 v7, v138
	v_mov_b32_e32 v8, v138
	v_mov_b32_e32 v9, v138
	v_mov_b32_e32 v10, v138
	v_mov_b32_e32 v11, v138
	v_mov_b32_e32 v12, v138
	v_mov_b32_e32 v13, v138
	v_mov_b32_e32 v14, v138
	v_mov_b32_e32 v15, v138
	v_mov_b32_e32 v16, v138
	v_mov_b32_e32 v17, v138
	v_mov_b32_e32 v18, 0
	v_mov_b32_e32 v19, v138
	v_mov_b32_e32 v20, v138
	v_mov_b32_e32 v21, v138
	v_mov_b32_e32 v22, v138
	v_mov_b32_e32 v23, v138
	v_mov_b32_e32 v24, v138
	v_mov_b32_e32 v25, v138
	v_mov_b32_e32 v26, v138
	v_mov_b32_e32 v27, v138
	v_mov_b32_e32 v28, v138
	v_mov_b32_e32 v29, v138
	v_mov_b32_e32 v30, v138
	v_mov_b32_e32 v31, v138
	v_mov_b32_e32 v32, v138
	v_mov_b32_e32 v33, v138
	v_mov_b32_e32 v34, 0
	v_mov_b32_e32 v35, v138
	v_mov_b32_e32 v36, v138
	v_mov_b32_e32 v37, v138
	v_mov_b32_e32 v38, v138
	v_mov_b32_e32 v39, v138
	v_mov_b32_e32 v40, v138
	v_mov_b32_e32 v41, v138
	v_mov_b32_e32 v42, v138
	v_mov_b32_e32 v43, v138
	v_mov_b32_e32 v44, v138
	v_mov_b32_e32 v45, v138
	v_mov_b32_e32 v46, v138
	v_mov_b32_e32 v47, v138
	v_mov_b32_e32 v48, v138
	v_mov_b32_e32 v49, v138
	v_mov_b32_e32 v50, 0
	v_mov_b32_e32 v51, v138
	v_mov_b32_e32 v52, v138
	v_mov_b32_e32 v53, v138
	v_mov_b32_e32 v54, v138
	v_mov_b32_e32 v55, v138
	v_mov_b32_e32 v56, v138
	v_mov_b32_e32 v57, v138
	v_mov_b32_e32 v58, v138
	v_mov_b32_e32 v59, v138
	v_mov_b32_e32 v60, v138
	v_mov_b32_e32 v61, v138
	v_mov_b32_e32 v62, v138
	v_mov_b32_e32 v63, v138
	v_mov_b32_e32 v64, v138
	v_mov_b32_e32 v65, v138
	global_load_dwordx2 v[176:177], v[136:137], off offset:-4
	v_lshl_add_u64 v[136:137], v[136:137], 0, 8
	s_waitcnt vmcnt(0) lgkmcnt(0)
	s_barrier
	s_cmp_lt_u32 s28, 4
	s_cbranch_scc1 .Ldsa1_pre
	s_barrier

.LBB0_2562:
	s_branch .LBB0_2561
.LBB0_2564:
	s_cmp_lt_u32 s28, 4
	s_cbranch_scc0 .Ldsa1_post
	s_barrier
